# adds G10 gate loads issued at K-loop exit and G9 phase prologue: eight gather-index loads issued together (were eight serialized round trips)
# speedup vs baseline: 1.0101x; 1.0041x over previous
; template <class Epi, bool GATHER = false>
; __device__ __forceinline__ void gemm_phase(LAS unsigned char* lds, const Gemm g, const Order& S, const Epi& E, const int* gidx = nullptr) {
;     ...
;     { int R, C; stage_rc(tid * 16, R, C); const int Rb = (R & ~31) + perm32(R & 31); voffA = (unsigned)(R * K + C) * 2u; voffB = (unsigned)(Rb * K + C) * 2u; Rl = R; C2 = C * 2; }
;     ...
;     if constexpr (GATHER) {
;         Unit u1; const bool h1 = S.next(1, u1);
; #pragma unroll
;         for (int q = 0; q < 4; ++q) { gc[q] = (unsigned)gidx[cur.pm * BM + q * 64 + Rl] * (unsigned)(K * 2) + (unsigned)C2; gn[q] = h1 ? (unsigned)gidx[u1.pm * BM + q * 64 + Rl] * (unsigned)(K * 2) + (unsigned)C2 : gc[q]; }
.LBB0_752:
	s_andn2_b64 vcc, exec, s[0:1]
	s_cbranch_vccnz .LBB0_836
	v_readlane_b32 s0, v254, 0
	v_readlane_b32 s4, v254, 18
	v_readlane_b32 s1, v254, 1
	v_mov_b32_e32 v4, v222
	v_readlane_b32 s5, v254, 19
	s_andn2_b64 vcc, exec, s[4:5]
	v_readfirstlane_b32 s4, v4
	s_cbranch_vccnz .LBB0_782
	v_ashrrev_i32_e32 v1, 31, v4
	v_lshrrev_b32_e32 v1, 26, v1
	v_add_u32_e32 v1, v4, v1
	v_ashrrev_i32_e32 v6, 6, v1
	v_bfe_i32 v1, v4, 27, 1
	v_lshlrev_b32_e32 v0, 4, v4
	v_lshrrev_b32_e32 v1, 22, v1
	v_add_u32_e32 v1, v0, v1
	v_and_b32_e32 v1, 0xfffffc00, v1
	v_sub_u32_e32 v0, v0, v1
	v_lshrrev_b32_e32 v1, 4, v0
	s_load_dwordx2 s[12:13], s[0:1], 0xb8
	v_bitop3_b32 v7, v1, v0, 32 bitop3:0x6c
	v_ashrrev_i32_e32 v0, 31, v0
	v_lshrrev_b32_e32 v0, 26, v0
	v_lshlrev_b32_e32 v1, 3, v6
	v_add_u32_e32 v0, v7, v0
	v_and_b32_e32 v1, -16, v1
	v_ashrrev_i32_e32 v5, 6, v0
	v_add_u32_e32 v138, v5, v1
	v_readlane_b32 s0, v254, 50
	s_waitcnt lgkmcnt(0)
	s_add_u32 s14, s12, 0x39300000
	s_addc_u32 s15, s13, 0
	v_add_u32_e32 v0, s0, v138
	v_ashrrev_i32_e32 v1, 31, v0
	v_lshl_add_u64 v[8:9], v[0:1], 2, s[14:15]
	global_load_dword v10, v[8:9], off
	global_load_dword v11, v[8:9], off offset:256
	global_load_dword v12, v[8:9], off offset:512
	global_load_dword v13, v[8:9], off offset:768
	v_readlane_b32 s0, v254, 46
	v_readlane_b32 s1, v254, 47
	v_readlane_b32 s5, v254, 48
	v_lshlrev_b32_e32 v2, 5, v6
	v_and_b32_e32 v3, 32, v2
	v_mul_i32_i24_e32 v2, 64, v5
	v_sub_u32_e32 v6, v7, v2
	v_ashrrev_i16_sdwa v6, v226, sext(v6) dst_sel:DWORD dst_unused:UNUSED_PAD src0_sel:DWORD src1_sel:BYTE_0
	v_bfe_i32 v6, v6, 0, 16
	v_add_lshl_u32 v139, v3, v6, 1
	v_add_u32_e32 v2, s5, v138
	v_cndmask_b32_e64 v2, v0, v2, s[0:1]
	v_ashrrev_i32_e32 v3, 31, v2
	v_lshl_add_u64 v[8:9], v[2:3], 2, s[14:15]
	global_load_dword v14, v[8:9], off
	global_load_dword v15, v[8:9], off offset:256
	global_load_dword v16, v[8:9], off offset:512
	global_load_dword v17, v[8:9], off offset:768
	s_waitcnt vmcnt(0)
	v_lshl_add_u32 v141, v10, 11, v139
	v_lshl_add_u32 v140, v14, 11, v139
	v_lshl_add_u32 v143, v11, 11, v139
	v_lshl_add_u32 v142, v15, 11, v139
	v_lshl_add_u32 v128, v12, 11, v139
	v_lshl_add_u32 v144, v16, 11, v139
	v_lshl_add_u32 v130, v13, 11, v139
	v_lshl_add_u32 v145, v17, 11, v139

; #define PG8_STAGE(bufoff, gbase, voff) do { _Pragma("unroll") for (int _i = 0; _i < 2; ++_i) \
;         __builtin_amdgcn_global_load_lds((const unsigned*)((const char*)(gbase) + _i * qstep + (voff)), (LAS unsigned*)(lds + (bufoff) + ldsw + _i * 8192), 16, 0, 0); } while (0)
; #define PG8_LDA(dst, b, h) do { _Pragma("unroll") for (int m = 0; m < 4; ++m) _Pragma("unroll") for (int k = 0; k < 2; ++k) dst[m][k] = *(const LAS bf16x8*)(lds + PG8_SA(b, h) + aoff + m * 2048 + k * 1024); } while (0)
; #define PG8_LDB(dst, b, h) do { _Pragma("unroll") for (int n = 0; n < 2; ++n) _Pragma("unroll") for (int k = 0; k < 2; ++k) dst[n][k] = *(const LAS bf16x8*)(lds + PG8_SB(b, h) + boff + n * 2048 + k * 1024); } while (0)
; #define PG8_MMA(ai, bj, At, Bt) do { __builtin_amdgcn_s_setprio(3); _Pragma("unroll") for (int m = 0; m < 4; ++m) _Pragma("unroll") for (int n = 0; n < 2; ++n) _Pragma("unroll") for (int k = 0; k < 2; ++k) \
;         acc[ai][bj][m][n] = __builtin_amdgcn_mfma_f32_16x16x32_bf16(Bt[n][k], At[m][k], acc[ai][bj][m][n], 0, 0, 0); __builtin_amdgcn_s_setprio(0); } while (0)
; #define PG8_WAIT_V(n) asm volatile("s_waitcnt vmcnt(" #n ")" ::: "memory")
; #define PG8_BAR __builtin_amdgcn_s_barrier()
; template <class Epi, bool GATHER = false>
; __device__ __forceinline__ void gemm_phase(LAS unsigned char* lds, const Gemm g, const Order& S, const Epi& E, const int* gidx = nullptr) {
;     ...
;         for (int t = 0; t < nt; t += 2) {
;             const bool last = (t == nt - 2);
;             if constexpr (Epi::HAS_MID) { if (t == Epi::MID_T) { PG8_SCHED; E.mid(acc, cur, wr, wc, fr, fq); PG8_SCHED; } }
;             const char* a1 = cA + (size_t)(t + 1) * kstep;
;             const char* a2 = last ? nA : cA + (size_t)(t + 2) * kstep; const char* b2 = last ? nB : cB + (size_t)(t + 2) * kstep;
;             const char* a3 = a2 + kstep; const char* b3 = b2 + kstep;
;             PG8_LDB(B0, 0, 0); PG8_LDB(B1, 0, 1); PG8_SCHED; PG8_LDA(At, 0, 0); PG8_STAGE_A(PG8_SA(1, 1), a1, 1, false);
;             PG8_WAIT_V(8); PG8_WAIT_L(0); PG8_BAR; PG8_MMA(0, 0, At, B0); PG8_MMA(0, 1, At, B1); PG8_BAR; PG8_SCHED;
;             PG8_LDA(At, 0, 1); PG8_STAGE(PG8_SB(0, 0), b2, voffB); PG8_STAGE(PG8_SB(0, 1), b2 + hstep, voffB); PG8_STAGE_A(PG8_SA(0, 0), a2, 0, last);
;             PG8_WAIT_V(8); PG8_WAIT_L(0); PG8_BAR; PG8_MMA(1, 0, At, B0); PG8_MMA(1, 1, At, B1); PG8_BAR; PG8_SCHED;
.LBB0_848:
	s_add_u32 s0, s24, 0xfff80080
	s_addc_u32 s1, s25, -1
	s_add_i32 s46, 0, 0x10000
	s_cmp_eq_u32 s81, 28
	s_cselect_b32 s1, s17, s1
	s_cselect_b32 s0, s52, s0
	s_cselect_b32 s51, s19, s5
	s_cselect_b32 s50, s53, s4
	s_add_i32 s61, 0, 0x14000
	v_add_u32_e32 v150, s46, v139
	v_add_u32_e32 v166, s61, v139
	ds_read_b128 v[134:137], v150
	ds_read_b128 v[142:145], v150 offset:1024
	ds_read_b128 v[146:149], v150 offset:2048
	ds_read_b128 v[150:153], v150 offset:3072
	ds_read_b128 v[154:157], v166
	ds_read_b128 v[158:161], v166 offset:1024
	ds_read_b128 v[162:165], v166 offset:2048
	ds_read_b128 v[166:169], v166 offset:3072
	v_lshl_add_u64 v[190:191], s[24:25], 0, v[132:133]
	s_add_i32 m0, s31, 0xc000
	ds_read_b128 v[170:173], v141
	ds_read_b128 v[174:177], v141 offset:1024
	ds_read_b128 v[178:181], v141 offset:2048
	ds_read_b128 v[182:185], v141 offset:3072
	ds_read_b128 v[186:189], v141 offset:4096
	ds_read_b128 v[212:215], v141 offset:5120
	ds_read_b128 v[216:219], v141 offset:6144
	ds_read_b128 v[236:239], v141 offset:7168
	global_load_lds_dwordx4 v[190:191], off
	v_lshl_add_u64 v[190:191], v[190:191], 0, s[92:93]
	s_add_i32 m0, s31, 0xe000
	s_nop 0
	global_load_lds_dwordx4 v[190:191], off
	s_waitcnt vmcnt(8)
	s_waitcnt lgkmcnt(0)
	s_barrier
	s_setprio 3
	s_waitcnt lgkmcnt(0)
	v_mfma_f32_16x16x32_bf16 v[124:127], v[134:137], v[170:173], v[124:127]
	v_mfma_f32_16x16x32_bf16 v[120:123], v[146:149], v[170:173], v[120:123]
	v_mfma_f32_16x16x32_bf16 v[108:111], v[134:137], v[178:181], v[108:111]
	v_mfma_f32_16x16x32_bf16 v[104:107], v[146:149], v[178:181], v[104:107]
	v_mfma_f32_16x16x32_bf16 v[92:95], v[134:137], v[186:189], v[92:95]
	v_mfma_f32_16x16x32_bf16 v[88:91], v[146:149], v[186:189], v[88:91]
	v_mfma_f32_16x16x32_bf16 v[76:79], v[134:137], v[216:219], v[76:79]
	v_mfma_f32_16x16x32_bf16 v[72:75], v[146:149], v[216:219], v[72:75]
	v_mfma_f32_16x16x32_bf16 v[124:127], v[142:145], v[174:177], v[124:127]
	v_mfma_f32_16x16x32_bf16 v[120:123], v[150:153], v[174:177], v[120:123]
	v_mfma_f32_16x16x32_bf16 v[108:111], v[142:145], v[182:185], v[108:111]
	v_mfma_f32_16x16x32_bf16 v[104:107], v[150:153], v[182:185], v[104:107]
	v_mfma_f32_16x16x32_bf16 v[92:95], v[142:145], v[212:215], v[92:95]
	v_mfma_f32_16x16x32_bf16 v[88:91], v[150:153], v[212:215], v[88:91]
	v_mfma_f32_16x16x32_bf16 v[76:79], v[142:145], v[236:239], v[76:79]
	v_mfma_f32_16x16x32_bf16 v[72:75], v[150:153], v[236:239], v[72:75]
	s_setprio 0
	s_setprio 3
	v_mfma_f32_16x16x32_bf16 v[116:119], v[154:157], v[170:173], v[116:119]
	v_mfma_f32_16x16x32_bf16 v[112:115], v[162:165], v[170:173], v[112:115]
	v_mfma_f32_16x16x32_bf16 v[100:103], v[154:157], v[178:181], v[100:103]
	v_mfma_f32_16x16x32_bf16 v[96:99], v[162:165], v[178:181], v[96:99]
	v_mfma_f32_16x16x32_bf16 v[84:87], v[154:157], v[186:189], v[84:87]
	v_mfma_f32_16x16x32_bf16 v[80:83], v[162:165], v[186:189], v[80:83]
	v_mfma_f32_16x16x32_bf16 v[68:71], v[154:157], v[216:219], v[68:71]
	v_mfma_f32_16x16x32_bf16 v[64:67], v[162:165], v[216:219], v[64:67]
	v_mfma_f32_16x16x32_bf16 v[116:119], v[158:161], v[174:177], v[116:119]
	v_mfma_f32_16x16x32_bf16 v[112:115], v[166:169], v[174:177], v[112:115]
	v_mfma_f32_16x16x32_bf16 v[100:103], v[158:161], v[182:185], v[100:103]
	v_mfma_f32_16x16x32_bf16 v[96:99], v[166:169], v[182:185], v[96:99]
	v_mfma_f32_16x16x32_bf16 v[84:87], v[158:161], v[212:215], v[84:87]
	v_mfma_f32_16x16x32_bf16 v[80:83], v[166:169], v[212:215], v[80:83]
	v_mfma_f32_16x16x32_bf16 v[68:71], v[158:161], v[236:239], v[68:71]
	v_mfma_f32_16x16x32_bf16 v[64:67], v[166:169], v[236:239], v[64:67]
	s_setprio 0
	s_barrier
	s_add_i32 s46, s46, s30
	v_lshl_add_u64 v[190:191], s[50:51], 0, v[128:129]
	s_mov_b32 m0, s46
	ds_read_b128 v[170:173], v141 offset:16384
	ds_read_b128 v[174:177], v141 offset:17408
	ds_read_b128 v[178:181], v141 offset:18432
	ds_read_b128 v[182:185], v141 offset:19456
	ds_read_b128 v[186:189], v141 offset:20480
	ds_read_b128 v[212:215], v141 offset:21504
	ds_read_b128 v[216:219], v141 offset:22528
	ds_read_b128 v[236:239], v141 offset:23552
	global_load_lds_dwordx4 v[190:191], off
	v_lshl_add_u64 v[220:221], v[190:191], 0, s[92:93]
	s_add_i32 m0, s46, 0x2000
	s_add_i32 s46, s61, s30
	global_load_lds_dwordx4 v[220:221], off
	v_lshl_add_u64 v[220:221], v[190:191], 0, s[66:67]
	s_mov_b32 m0, s46
	s_nop 0
	global_load_lds_dwordx4 v[220:221], off
	v_lshl_add_u64 v[220:221], v[190:191], 0, s[68:69]
	s_add_i32 m0, s46, 0x2000
	s_nop 0
	global_load_lds_dwordx4 v[220:221], off
	v_lshl_add_u64 v[220:221], s[0:1], 0, v[130:131]
	s_mov_b32 m0, s31
	v_lshl_add_u64 v[224:225], v[220:221], 0, s[92:93]
	global_load_lds_dwordx4 v[220:221], off
	s_mov_b32 m0, s34
	s_nop 0
	global_load_lds_dwordx4 v[224:225], off
	s_waitcnt vmcnt(8)
	s_waitcnt lgkmcnt(0)
	s_barrier
; #define PG8_STAGE(bufoff, gbase, voff) do { _Pragma("unroll") for (int _i = 0; _i < 2; ++_i) \
;         __builtin_amdgcn_global_load_lds((const unsigned*)((const char*)(gbase) + _i * qstep + (voff)), (LAS unsigned*)(lds + (bufoff) + ldsw + _i * 8192), 16, 0, 0); } while (0)
; #define PG8_LDA(dst, b, h) do { _Pragma("unroll") for (int m = 0; m < 4; ++m) _Pragma("unroll") for (int k = 0; k < 2; ++k) dst[m][k] = *(const LAS bf16x8*)(lds + PG8_SA(b, h) + aoff + m * 2048 + k * 1024); } while (0)
; #define PG8_LDB(dst, b, h) do { _Pragma("unroll") for (int n = 0; n < 2; ++n) _Pragma("unroll") for (int k = 0; k < 2; ++k) dst[n][k] = *(const LAS bf16x8*)(lds + PG8_SB(b, h) + boff + n * 2048 + k * 1024); } while (0)
; #define PG8_MMA(ai, bj, At, Bt) do { __builtin_amdgcn_s_setprio(3); _Pragma("unroll") for (int m = 0; m < 4; ++m) _Pragma("unroll") for (int n = 0; n < 2; ++n) _Pragma("unroll") for (int k = 0; k < 2; ++k) \
;         acc[ai][bj][m][n] = __builtin_amdgcn_mfma_f32_16x16x32_bf16(Bt[n][k], At[m][k], acc[ai][bj][m][n], 0, 0, 0); __builtin_amdgcn_s_setprio(0); } while (0)
; #define PG8_WAIT_V(n) asm volatile("s_waitcnt vmcnt(" #n ")" ::: "memory")
; #define PG8_WAIT_L(n) asm volatile("s_waitcnt lgkmcnt(" #n ")" ::: "memory")
; #define PG8_BAR __builtin_amdgcn_s_barrier()
; #define PG8_SCHED __builtin_amdgcn_sched_barrier(0)
; template <class Epi, bool GATHER = false>
; __device__ __forceinline__ void gemm_phase(LAS unsigned char* lds, const Gemm g, const Order& S, const Epi& E, const int* gidx = nullptr) {
;     ...
;             PG8_WAIT_V(8); PG8_WAIT_L(0); PG8_BAR; PG8_MMA(1, 0, At, B0); PG8_MMA(1, 1, At, B1); PG8_BAR; PG8_SCHED;
;             PG8_LDB(B0, 1, 0); PG8_LDB(B1, 1, 1); PG8_SCHED; PG8_LDA(At, 1, 0); PG8_STAGE_A(PG8_SA(0, 1), a2, 1, last);
;             PG8_WAIT_V(8); PG8_WAIT_L(0); PG8_BAR; PG8_MMA(0, 0, At, B0); PG8_MMA(0, 1, At, B1); PG8_BAR; PG8_SCHED;
;             PG8_LDA(At, 1, 1); PG8_STAGE(PG8_SB(1, 0), b3, voffB); PG8_STAGE(PG8_SB(1, 1), b3 + hstep, voffB); PG8_STAGE_A(PG8_SA(1, 0), a3, 0, last);
	s_setprio 3
	s_waitcnt lgkmcnt(0)
	v_mfma_f32_16x16x32_bf16 v[60:63], v[134:137], v[170:173], v[60:63]
	v_mfma_f32_16x16x32_bf16 v[56:59], v[146:149], v[170:173], v[56:59]
	v_mfma_f32_16x16x32_bf16 v[44:47], v[134:137], v[178:181], v[44:47]
	v_mfma_f32_16x16x32_bf16 v[40:43], v[146:149], v[178:181], v[40:43]
	v_mfma_f32_16x16x32_bf16 v[28:31], v[134:137], v[186:189], v[28:31]
	v_mfma_f32_16x16x32_bf16 v[24:27], v[146:149], v[186:189], v[24:27]
	v_mfma_f32_16x16x32_bf16 v[12:15], v[134:137], v[216:219], v[12:15]
	v_mfma_f32_16x16x32_bf16 v[8:11], v[146:149], v[216:219], v[8:11]
	v_mfma_f32_16x16x32_bf16 v[60:63], v[142:145], v[174:177], v[60:63]
	v_mfma_f32_16x16x32_bf16 v[56:59], v[150:153], v[174:177], v[56:59]
	v_mfma_f32_16x16x32_bf16 v[44:47], v[142:145], v[182:185], v[44:47]
	v_mfma_f32_16x16x32_bf16 v[40:43], v[150:153], v[182:185], v[40:43]
	v_mfma_f32_16x16x32_bf16 v[28:31], v[142:145], v[212:215], v[28:31]
	v_mfma_f32_16x16x32_bf16 v[24:27], v[150:153], v[212:215], v[24:27]
	v_mfma_f32_16x16x32_bf16 v[12:15], v[142:145], v[236:239], v[12:15]
	v_mfma_f32_16x16x32_bf16 v[8:11], v[150:153], v[236:239], v[8:11]
	s_setprio 0
	s_setprio 3
	v_mfma_f32_16x16x32_bf16 v[52:55], v[154:157], v[170:173], v[52:55]
	v_mfma_f32_16x16x32_bf16 v[48:51], v[162:165], v[170:173], v[48:51]
	v_mfma_f32_16x16x32_bf16 v[36:39], v[154:157], v[178:181], v[36:39]
	v_mfma_f32_16x16x32_bf16 v[32:35], v[162:165], v[178:181], v[32:35]
	v_mfma_f32_16x16x32_bf16 v[20:23], v[154:157], v[186:189], v[20:23]
	v_mfma_f32_16x16x32_bf16 v[16:19], v[162:165], v[186:189], v[16:19]
	v_mfma_f32_16x16x32_bf16 v[4:7], v[154:157], v[216:219], v[4:7]
	v_mfma_f32_16x16x32_bf16 v[0:3], v[162:165], v[216:219], v[0:3]
	v_mfma_f32_16x16x32_bf16 v[52:55], v[158:161], v[174:177], v[52:55]
	v_mfma_f32_16x16x32_bf16 v[48:51], v[166:169], v[174:177], v[48:51]
	v_mfma_f32_16x16x32_bf16 v[36:39], v[158:161], v[182:185], v[36:39]
	v_mfma_f32_16x16x32_bf16 v[32:35], v[166:169], v[182:185], v[32:35]
	v_mfma_f32_16x16x32_bf16 v[20:23], v[158:161], v[212:215], v[20:23]
	v_mfma_f32_16x16x32_bf16 v[16:19], v[166:169], v[212:215], v[16:19]
	v_mfma_f32_16x16x32_bf16 v[4:7], v[158:161], v[236:239], v[4:7]
	v_mfma_f32_16x16x32_bf16 v[0:3], v[166:169], v[236:239], v[0:3]
	s_setprio 0
	s_barrier
	s_add_i32 s0, 0, 0x18000
	s_add_i32 s1, 0, 0x1c000
	v_add_u32_e32 v150, s0, v139
	v_add_u32_e32 v166, s1, v139
	ds_read_b128 v[134:137], v150
	ds_read_b128 v[142:145], v150 offset:1024
	ds_read_b128 v[146:149], v150 offset:2048
	ds_read_b128 v[150:153], v150 offset:3072
	ds_read_b128 v[154:157], v166
	ds_read_b128 v[158:161], v166 offset:1024
	ds_read_b128 v[162:165], v166 offset:2048
	ds_read_b128 v[166:169], v166 offset:3072
	s_mov_b32 m0, s35
	v_lshl_add_u64 v[224:225], v[220:221], 0, s[66:67]
	ds_read_b128 v[170:173], v141 offset:32768
	ds_read_b128 v[174:177], v141 offset:33792
	ds_read_b128 v[178:181], v141 offset:34816
	ds_read_b128 v[182:185], v141 offset:35840
	ds_read_b128 v[186:189], v141 offset:36864
	ds_read_b128 v[212:215], v141 offset:37888
	ds_read_b128 v[216:219], v141 offset:38912
	ds_read_b128 v[236:239], v141 offset:39936
	global_load_lds_dwordx4 v[224:225], off
	v_lshl_add_u64 v[224:225], v[220:221], 0, s[68:69]
	s_mov_b32 m0, s36
	s_nop 0
	global_load_lds_dwordx4 v[224:225], off
	s_waitcnt vmcnt(8)
	s_waitcnt lgkmcnt(0)
	s_barrier
	s_setprio 3
	s_waitcnt lgkmcnt(0)
	v_mfma_f32_16x16x32_bf16 v[124:127], v[134:137], v[170:173], v[124:127]
	v_mfma_f32_16x16x32_bf16 v[120:123], v[146:149], v[170:173], v[120:123]
	v_mfma_f32_16x16x32_bf16 v[108:111], v[134:137], v[178:181], v[108:111]
	v_mfma_f32_16x16x32_bf16 v[104:107], v[146:149], v[178:181], v[104:107]
	v_mfma_f32_16x16x32_bf16 v[92:95], v[134:137], v[186:189], v[92:95]
	v_mfma_f32_16x16x32_bf16 v[88:91], v[146:149], v[186:189], v[88:91]
	v_mfma_f32_16x16x32_bf16 v[76:79], v[134:137], v[216:219], v[76:79]
	v_mfma_f32_16x16x32_bf16 v[72:75], v[146:149], v[216:219], v[72:75]
	v_mfma_f32_16x16x32_bf16 v[124:127], v[142:145], v[174:177], v[124:127]
	v_mfma_f32_16x16x32_bf16 v[120:123], v[150:153], v[174:177], v[120:123]
	v_mfma_f32_16x16x32_bf16 v[108:111], v[142:145], v[182:185], v[108:111]
	v_mfma_f32_16x16x32_bf16 v[104:107], v[150:153], v[182:185], v[104:107]
	v_mfma_f32_16x16x32_bf16 v[92:95], v[142:145], v[212:215], v[92:95]
	v_mfma_f32_16x16x32_bf16 v[88:91], v[150:153], v[212:215], v[88:91]
	v_mfma_f32_16x16x32_bf16 v[76:79], v[142:145], v[236:239], v[76:79]
	v_mfma_f32_16x16x32_bf16 v[72:75], v[150:153], v[236:239], v[72:75]
	s_setprio 0
	s_setprio 3
	v_mfma_f32_16x16x32_bf16 v[116:119], v[154:157], v[170:173], v[116:119]
	v_mfma_f32_16x16x32_bf16 v[112:115], v[162:165], v[170:173], v[112:115]
	v_mfma_f32_16x16x32_bf16 v[100:103], v[154:157], v[178:181], v[100:103]
	v_mfma_f32_16x16x32_bf16 v[96:99], v[162:165], v[178:181], v[96:99]
	v_mfma_f32_16x16x32_bf16 v[84:87], v[154:157], v[186:189], v[84:87]
	v_mfma_f32_16x16x32_bf16 v[80:83], v[162:165], v[186:189], v[80:83]
	v_mfma_f32_16x16x32_bf16 v[68:71], v[154:157], v[216:219], v[68:71]
	v_mfma_f32_16x16x32_bf16 v[64:67], v[162:165], v[216:219], v[64:67]
	v_mfma_f32_16x16x32_bf16 v[116:119], v[158:161], v[174:177], v[116:119]
	v_mfma_f32_16x16x32_bf16 v[112:115], v[166:169], v[174:177], v[112:115]
	v_mfma_f32_16x16x32_bf16 v[100:103], v[158:161], v[182:185], v[100:103]
	v_mfma_f32_16x16x32_bf16 v[96:99], v[166:169], v[182:185], v[96:99]
	v_mfma_f32_16x16x32_bf16 v[84:87], v[158:161], v[212:215], v[84:87]
	v_mfma_f32_16x16x32_bf16 v[80:83], v[166:169], v[212:215], v[80:83]
	v_mfma_f32_16x16x32_bf16 v[68:71], v[158:161], v[236:239], v[68:71]
	v_mfma_f32_16x16x32_bf16 v[64:67], v[166:169], v[236:239], v[64:67]
	s_setprio 0
	s_barrier
; #define PG8_STAGE(bufoff, gbase, voff) do { _Pragma("unroll") for (int _i = 0; _i < 2; ++_i) \
;         __builtin_amdgcn_global_load_lds((const unsigned*)((const char*)(gbase) + _i * qstep + (voff)), (LAS unsigned*)(lds + (bufoff) + ldsw + _i * 8192), 16, 0, 0); } while (0)
; #define PG8_LDA(dst, b, h) do { _Pragma("unroll") for (int m = 0; m < 4; ++m) _Pragma("unroll") for (int k = 0; k < 2; ++k) dst[m][k] = *(const LAS bf16x8*)(lds + PG8_SA(b, h) + aoff + m * 2048 + k * 1024); } while (0)
; #define PG8_MMA(ai, bj, At, Bt) do { __builtin_amdgcn_s_setprio(3); _Pragma("unroll") for (int m = 0; m < 4; ++m) _Pragma("unroll") for (int n = 0; n < 2; ++n) _Pragma("unroll") for (int k = 0; k < 2; ++k) \
;         acc[ai][bj][m][n] = __builtin_amdgcn_mfma_f32_16x16x32_bf16(Bt[n][k], At[m][k], acc[ai][bj][m][n], 0, 0, 0); __builtin_amdgcn_s_setprio(0); } while (0)
; #define PG8_WAIT_V(n) asm volatile("s_waitcnt vmcnt(" #n ")" ::: "memory")
; #define PG8_WAIT_L(n) asm volatile("s_waitcnt lgkmcnt(" #n ")" ::: "memory")
; #define PG8_BAR __builtin_amdgcn_s_barrier()
; #define PG8_SCHED __builtin_amdgcn_sched_barrier(0)
; template <class Epi, bool GATHER = false>
; __device__ __forceinline__ void gemm_phase(LAS unsigned char* lds, const Gemm g, const Order& S, const Epi& E, const int* gidx = nullptr) {
;     ...
;             PG8_LDA(At, 1, 1); PG8_STAGE(PG8_SB(1, 0), b3, voffB); PG8_STAGE(PG8_SB(1, 1), b3 + hstep, voffB); PG8_STAGE_A(PG8_SA(1, 0), a3, 0, last);
;             PG8_WAIT_V(8); PG8_WAIT_L(0); PG8_BAR; PG8_MMA(1, 0, At, B0); PG8_MMA(1, 1, At, B1); PG8_BAR; PG8_SCHED;
;         }
;         if (wr == 0) PG8_BAR;
;     __device__ __forceinline__ void operator()(const f32x4 (&acc)[2][2][4][2], const Unit& u, int wr, int wc, int fr, int fq) const {
;     ...
;             for (int m = 0; m < 4; ++m) { const size_t r = (size_t)(row0 + ai * HALF + m * 16); const float gt = gate[r];
	s_add_i32 s0, s0, s30
	v_lshl_add_u64 v[224:225], v[190:191], 0, s[96:97]
	s_mov_b32 m0, s0
	ds_read_b128 v[170:173], v141 offset:49152
	ds_read_b128 v[174:177], v141 offset:50176
	ds_read_b128 v[178:181], v141 offset:51200
	ds_read_b128 v[182:185], v141 offset:52224
	ds_read_b128 v[186:189], v141 offset:53248
	ds_read_b128 v[212:215], v141 offset:54272
	ds_read_b128 v[216:219], v141 offset:55296
	ds_read_b128 v[236:239], v141 offset:56320
	global_load_lds_dwordx4 v[224:225], off
	v_lshl_add_u64 v[224:225], v[190:191], 0, s[62:63]
	s_add_i32 m0, s0, 0x2000
	s_add_i32 s0, s1, s30
	global_load_lds_dwordx4 v[224:225], off
	v_lshl_add_u64 v[224:225], v[190:191], 0, s[74:75]
	s_mov_b32 m0, s0
	v_lshl_add_u64 v[190:191], v[190:191], 0, s[76:77]
	global_load_lds_dwordx4 v[224:225], off
	s_add_i32 m0, s0, 0x2000
	s_nop 0
	global_load_lds_dwordx4 v[190:191], off
	v_lshl_add_u64 v[190:191], v[220:221], 0, s[96:97]
	s_mov_b32 m0, s37
	s_nop 0
	global_load_lds_dwordx4 v[190:191], off
	v_lshl_add_u64 v[190:191], v[220:221], 0, s[62:63]
	s_mov_b32 m0, s38
	s_nop 0
	global_load_lds_dwordx4 v[190:191], off
	s_waitcnt vmcnt(8)
	s_waitcnt lgkmcnt(0)
	s_barrier
	s_setprio 3
	s_waitcnt lgkmcnt(0)
	v_mfma_f32_16x16x32_bf16 v[60:63], v[134:137], v[170:173], v[60:63]
	v_mfma_f32_16x16x32_bf16 v[56:59], v[146:149], v[170:173], v[56:59]
	v_mfma_f32_16x16x32_bf16 v[44:47], v[134:137], v[178:181], v[44:47]
	v_mfma_f32_16x16x32_bf16 v[40:43], v[146:149], v[178:181], v[40:43]
	v_mfma_f32_16x16x32_bf16 v[28:31], v[134:137], v[186:189], v[28:31]
	v_mfma_f32_16x16x32_bf16 v[24:27], v[146:149], v[186:189], v[24:27]
	v_mfma_f32_16x16x32_bf16 v[12:15], v[134:137], v[216:219], v[12:15]
	v_mfma_f32_16x16x32_bf16 v[8:11], v[146:149], v[216:219], v[8:11]
	v_mfma_f32_16x16x32_bf16 v[60:63], v[142:145], v[174:177], v[60:63]
	v_mfma_f32_16x16x32_bf16 v[56:59], v[150:153], v[174:177], v[56:59]
	v_mfma_f32_16x16x32_bf16 v[44:47], v[142:145], v[182:185], v[44:47]
	v_mfma_f32_16x16x32_bf16 v[40:43], v[150:153], v[182:185], v[40:43]
	v_mfma_f32_16x16x32_bf16 v[28:31], v[142:145], v[212:215], v[28:31]
	v_mfma_f32_16x16x32_bf16 v[24:27], v[150:153], v[212:215], v[24:27]
	v_mfma_f32_16x16x32_bf16 v[12:15], v[142:145], v[236:239], v[12:15]
	v_mfma_f32_16x16x32_bf16 v[8:11], v[150:153], v[236:239], v[8:11]
	s_setprio 0
	s_setprio 3
	v_mfma_f32_16x16x32_bf16 v[52:55], v[154:157], v[170:173], v[52:55]
	v_mfma_f32_16x16x32_bf16 v[48:51], v[162:165], v[170:173], v[48:51]
	v_mfma_f32_16x16x32_bf16 v[36:39], v[154:157], v[178:181], v[36:39]
	v_mfma_f32_16x16x32_bf16 v[32:35], v[162:165], v[178:181], v[32:35]
	v_mfma_f32_16x16x32_bf16 v[20:23], v[154:157], v[186:189], v[20:23]
	v_mfma_f32_16x16x32_bf16 v[16:19], v[162:165], v[186:189], v[16:19]
	v_mfma_f32_16x16x32_bf16 v[4:7], v[154:157], v[216:219], v[4:7]
	v_mfma_f32_16x16x32_bf16 v[0:3], v[162:165], v[216:219], v[0:3]
	v_mfma_f32_16x16x32_bf16 v[52:55], v[158:161], v[174:177], v[52:55]
	v_mfma_f32_16x16x32_bf16 v[48:51], v[166:169], v[174:177], v[48:51]
	v_mfma_f32_16x16x32_bf16 v[36:39], v[158:161], v[182:185], v[36:39]
	v_mfma_f32_16x16x32_bf16 v[32:35], v[166:169], v[182:185], v[32:35]
	v_mfma_f32_16x16x32_bf16 v[20:23], v[158:161], v[212:215], v[20:23]
	v_mfma_f32_16x16x32_bf16 v[16:19], v[166:169], v[212:215], v[16:19]
	v_mfma_f32_16x16x32_bf16 v[4:7], v[158:161], v[236:239], v[4:7]
	v_mfma_f32_16x16x32_bf16 v[0:3], v[166:169], v[236:239], v[0:3]
	s_setprio 0
	s_barrier
	s_add_i32 s81, s81, 2
	s_add_u32 s24, s24, 0x100
	s_addc_u32 s25, s25, 0
	s_add_u32 s4, s4, 0x100
	s_addc_u32 s5, s5, 0
	s_cmp_gt_u32 s81, 29
	s_cbranch_scc0 .LBB0_848
	v_lshl_add_u32 v136, s41, 8, v138
	v_ashrrev_i32_e32 v137, 31, v136
	v_lshl_add_u64 v[134:135], v[136:137], 2, s[12:13]
	global_load_dword v150, v[134:135], off
	global_load_dword v151, v[134:135], off offset:64
	global_load_dword v152, v[134:135], off offset:128
	global_load_dword v153, v[134:135], off offset:192
	global_load_dword v154, v[134:135], off offset:512
	global_load_dword v155, v[134:135], off offset:576
	global_load_dword v156, v[134:135], off offset:640
	global_load_dword v157, v[134:135], off offset:704
	s_and_b64 vcc, exec, s[14:15]
	s_cbranch_vccz .LBB0_851
	s_barrier
.LBB0_851:
	s_lshl_b32 s0, s40, 8
	s_and_b32 s0, s0, 0x300
	v_or_b32_e32 v143, s0, v140
	v_lshlrev_b64 v[144:145], 11, v[136:137]
	v_lshlrev_b32_e32 v194, 1, v143
	s_mov_b32 s0, 0x40000
	s_waitcnt vmcnt(0)
; __device__ __forceinline__ unsigned cvt_pk_bf16(float lo, float hi) { unsigned r; asm volatile("v_cvt_pk_bf16_f32 %0, %1, %2" : "=v"(r) : "v"(lo), "v"(hi)); return r; }
;     __device__ __forceinline__ void operator()(const f32x4 (&acc)[2][2][4][2], const Unit& u, int wr, int wc, int fr, int fq) const {
;     ...
;             for (int m = 0; m < 4; ++m) { const size_t r = (size_t)(row0 + ai * HALF + m * 16); const float gt = gate[r];
; #pragma unroll
;                 for (int bj = 0; bj < 2; ++bj) { const f32x4 v0 = acc[ai][bj][m][0] * gt, v1 = acc[ai][bj][m][1] * gt;
;                     u32x4 w; w.x = cvt_pk_bf16(v0[0], v0[1]); w.y = cvt_pk_bf16(v0[2], v0[3]); w.z = cvt_pk_bf16(v1[0], v1[1]); w.w = cvt_pk_bf16(v1[2], v1[3]);
;                     *(u32x4*)(ye + r * 1024 + col0 + bj * HALF) = w; } }
	v_mov_b32_e32 v142, v150
	v_pk_mul_f32 v[124:125], v[124:125], v[142:143] op_sel_hi:[1,0]
	v_pk_mul_f32 v[120:121], v[120:121], v[142:143] op_sel_hi:[1,0]
	v_pk_mul_f32 v[126:127], v[126:127], v[142:143] op_sel_hi:[1,0]
	v_pk_mul_f32 v[146:147], v[122:123], v[142:143] op_sel_hi:[1,0]
	v_cvt_pk_bf16_f32 v122, v124, v125
	v_cvt_pk_bf16_f32 v123, v126, v127
	v_cvt_pk_bf16_f32 v124, v120, v121
	v_lshl_add_u64 v[120:121], s[10:11], 0, v[144:145]
	v_lshl_add_u64 v[120:121], v[120:121], 0, v[194:195]
	v_cvt_pk_bf16_f32 v125, v146, v147
	global_store_dwordx4 v[120:121], v[122:125], off
	v_pk_mul_f32 v[116:117], v[116:117], v[142:143] op_sel_hi:[1,0]
	v_pk_mul_f32 v[118:119], v[118:119], v[142:143] op_sel_hi:[1,0]
	v_pk_mul_f32 v[122:123], v[114:115], v[142:143] op_sel_hi:[1,0]
	v_pk_mul_f32 v[114:115], v[112:113], v[142:143] op_sel_hi:[1,0]
	v_cvt_pk_bf16_f32 v112, v116, v117
	v_cvt_pk_bf16_f32 v113, v118, v119
	s_nop 0
	v_cvt_pk_bf16_f32 v114, v114, v115
	v_cvt_pk_bf16_f32 v115, v122, v123
	global_store_dwordx4 v[120:121], v[112:115], off offset:256
	s_nop 1
	v_or_b32_e32 v112, 16, v136
	v_ashrrev_i32_e32 v113, 31, v112
	v_lshl_add_u64 v[114:115], v[112:113], 2, s[12:13]
	v_mov_b32_e32 v114, v151
	v_lshlrev_b64 v[112:113], 11, v[112:113]
	v_pk_mul_f32 v[108:109], v[108:109], v[114:115] op_sel_hi:[1,0]
	v_pk_mul_f32 v[116:117], v[106:107], v[114:115] op_sel_hi:[1,0]
	v_pk_mul_f32 v[106:107], v[104:105], v[114:115] op_sel_hi:[1,0]
	v_cvt_pk_bf16_f32 v104, v108, v109
	v_lshl_add_u64 v[108:109], s[10:11], 0, v[112:113]
	v_pk_mul_f32 v[110:111], v[110:111], v[114:115] op_sel_hi:[1,0]
	v_lshl_add_u64 v[108:109], v[108:109], 0, v[194:195]
	v_cvt_pk_bf16_f32 v105, v110, v111
	v_cvt_pk_bf16_f32 v106, v106, v107
	v_cvt_pk_bf16_f32 v107, v116, v117
	global_store_dwordx4 v[108:109], v[104:107], off
	v_pk_mul_f32 v[100:101], v[100:101], v[114:115] op_sel_hi:[1,0]
	v_pk_mul_f32 v[102:103], v[102:103], v[114:115] op_sel_hi:[1,0]
	v_pk_mul_f32 v[104:105], v[98:99], v[114:115] op_sel_hi:[1,0]
	v_pk_mul_f32 v[98:99], v[96:97], v[114:115] op_sel_hi:[1,0]
	v_cvt_pk_bf16_f32 v96, v100, v101
	v_cvt_pk_bf16_f32 v97, v102, v103
	s_nop 0
	v_cvt_pk_bf16_f32 v98, v98, v99
	v_cvt_pk_bf16_f32 v99, v104, v105
	global_store_dwordx4 v[108:109], v[96:99], off offset:256
	s_nop 1
	v_or_b32_e32 v96, 32, v136
	v_ashrrev_i32_e32 v97, 31, v96
	v_lshl_add_u64 v[98:99], v[96:97], 2, s[12:13]
	v_mov_b32_e32 v98, v152
	v_lshlrev_b64 v[96:97], 11, v[96:97]
	v_pk_mul_f32 v[92:93], v[92:93], v[98:99] op_sel_hi:[1,0]
	v_pk_mul_f32 v[100:101], v[90:91], v[98:99] op_sel_hi:[1,0]
	v_pk_mul_f32 v[90:91], v[88:89], v[98:99] op_sel_hi:[1,0]
	v_cvt_pk_bf16_f32 v88, v92, v93
	v_lshl_add_u64 v[92:93], s[10:11], 0, v[96:97]
	v_pk_mul_f32 v[94:95], v[94:95], v[98:99] op_sel_hi:[1,0]
	v_lshl_add_u64 v[92:93], v[92:93], 0, v[194:195]
	v_cvt_pk_bf16_f32 v89, v94, v95
	v_cvt_pk_bf16_f32 v90, v90, v91
	v_cvt_pk_bf16_f32 v91, v100, v101
	global_store_dwordx4 v[92:93], v[88:91], off
	v_pk_mul_f32 v[84:85], v[84:85], v[98:99] op_sel_hi:[1,0]
	v_pk_mul_f32 v[86:87], v[86:87], v[98:99] op_sel_hi:[1,0]
	v_pk_mul_f32 v[88:89], v[82:83], v[98:99] op_sel_hi:[1,0]
	v_pk_mul_f32 v[82:83], v[80:81], v[98:99] op_sel_hi:[1,0]
	v_cvt_pk_bf16_f32 v80, v84, v85
	v_cvt_pk_bf16_f32 v81, v86, v87
	s_nop 0
	v_cvt_pk_bf16_f32 v82, v82, v83
	v_cvt_pk_bf16_f32 v83, v88, v89
	global_store_dwordx4 v[92:93], v[80:83], off offset:256
	s_nop 1
	v_or_b32_e32 v80, 48, v136
	v_ashrrev_i32_e32 v81, 31, v80
	v_lshl_add_u64 v[82:83], v[80:81], 2, s[12:13]
	v_mov_b32_e32 v82, v153
	v_lshlrev_b64 v[80:81], 11, v[80:81]
	v_pk_mul_f32 v[76:77], v[76:77], v[82:83] op_sel_hi:[1,0]
	v_pk_mul_f32 v[84:85], v[74:75], v[82:83] op_sel_hi:[1,0]
	v_pk_mul_f32 v[74:75], v[72:73], v[82:83] op_sel_hi:[1,0]
	v_cvt_pk_bf16_f32 v72, v76, v77
	v_lshl_add_u64 v[76:77], s[10:11], 0, v[80:81]
	v_pk_mul_f32 v[78:79], v[78:79], v[82:83] op_sel_hi:[1,0]
	v_lshl_add_u64 v[76:77], v[76:77], 0, v[194:195]
	v_cvt_pk_bf16_f32 v73, v78, v79
	v_cvt_pk_bf16_f32 v74, v74, v75
	v_cvt_pk_bf16_f32 v75, v84, v85
	global_store_dwordx4 v[76:77], v[72:75], off
	v_pk_mul_f32 v[70:71], v[70:71], v[82:83] op_sel_hi:[1,0]
	v_pk_mul_f32 v[68:69], v[68:69], v[82:83] op_sel_hi:[1,0]
	v_pk_mul_f32 v[72:73], v[66:67], v[82:83] op_sel_hi:[1,0]
	v_pk_mul_f32 v[66:67], v[64:65], v[82:83] op_sel_hi:[1,0]
	v_cvt_pk_bf16_f32 v64, v68, v69
	v_cvt_pk_bf16_f32 v65, v70, v71
	s_nop 0
	v_cvt_pk_bf16_f32 v66, v66, v67
; __device__ __forceinline__ unsigned cvt_pk_bf16(float lo, float hi) { unsigned r; asm volatile("v_cvt_pk_bf16_f32 %0, %1, %2" : "=v"(r) : "v"(lo), "v"(hi)); return r; }
;     __device__ __forceinline__ void operator()(const f32x4 (&acc)[2][2][4][2], const Unit& u, int wr, int wc, int fr, int fq) const {
;     ...
;             for (int m = 0; m < 4; ++m) { const size_t r = (size_t)(row0 + ai * HALF + m * 16); const float gt = gate[r];
; #pragma unroll
;                 for (int bj = 0; bj < 2; ++bj) { const f32x4 v0 = acc[ai][bj][m][0] * gt, v1 = acc[ai][bj][m][1] * gt;
;                     u32x4 w; w.x = cvt_pk_bf16(v0[0], v0[1]); w.y = cvt_pk_bf16(v0[2], v0[3]); w.z = cvt_pk_bf16(v1[0], v1[1]); w.w = cvt_pk_bf16(v1[2], v1[3]);
;                     *(u32x4*)(ye + r * 1024 + col0 + bj * HALF) = w; } }
	v_cvt_pk_bf16_f32 v67, v72, v73
	global_store_dwordx4 v[76:77], v[64:67], off offset:256
	s_nop 1
	v_mov_b32_e32 v64, v154
	v_pk_mul_f32 v[62:63], v[62:63], v[64:65] op_sel_hi:[1,0]
	v_pk_mul_f32 v[60:61], v[60:61], v[64:65] op_sel_hi:[1,0]
	v_pk_mul_f32 v[66:67], v[58:59], v[64:65] op_sel_hi:[1,0]
	v_pk_mul_f32 v[58:59], v[56:57], v[64:65] op_sel_hi:[1,0]
	v_cvt_pk_bf16_f32 v56, v60, v61
	v_cvt_pk_bf16_f32 v57, v62, v63
	v_add_co_u32_e32 v62, vcc, s0, v120
	v_cvt_pk_bf16_f32 v58, v58, v59
	v_cvt_pk_bf16_f32 v59, v66, v67
	v_lshl_add_u64 v[60:61], v[120:121], 0, s[92:93]
	s_nop 0
	v_addc_co_u32_e32 v63, vcc, 0, v121, vcc
	global_store_dwordx4 v[62:63], v[56:59], off
	v_pk_mul_f32 v[54:55], v[54:55], v[64:65] op_sel_hi:[1,0]
	v_pk_mul_f32 v[52:53], v[52:53], v[64:65] op_sel_hi:[1,0]
	v_pk_mul_f32 v[56:57], v[50:51], v[64:65] op_sel_hi:[1,0]
	v_pk_mul_f32 v[50:51], v[48:49], v[64:65] op_sel_hi:[1,0]
	v_cvt_pk_bf16_f32 v48, v52, v53
	v_cvt_pk_bf16_f32 v49, v54, v55
	s_mov_b64 s[0:1], 0x48000
	v_cvt_pk_bf16_f32 v50, v50, v51
	v_cvt_pk_bf16_f32 v51, v56, v57
	global_store_dwordx4 v[60:61], v[48:51], off offset:256
	s_nop 1
	v_mov_b32_e32 v48, v155
	v_pk_mul_f32 v[44:45], v[44:45], v[48:49] op_sel_hi:[1,0]
	v_pk_mul_f32 v[46:47], v[46:47], v[48:49] op_sel_hi:[1,0]
	v_pk_mul_f32 v[50:51], v[42:43], v[48:49] op_sel_hi:[1,0]
	v_pk_mul_f32 v[42:43], v[40:41], v[48:49] op_sel_hi:[1,0]
	v_cvt_pk_bf16_f32 v40, v44, v45
	v_lshl_add_u64 v[44:45], v[120:121], 0, s[0:1]
	s_mov_b32 s0, 0x48000
	v_cvt_pk_bf16_f32 v41, v46, v47
	v_add_co_u32_e32 v46, vcc, s0, v120
	v_cvt_pk_bf16_f32 v42, v42, v43
	v_cvt_pk_bf16_f32 v43, v50, v51
	v_pk_mul_f32 v[38:39], v[38:39], v[48:49] op_sel_hi:[1,0]
	s_nop 0
	v_addc_co_u32_e32 v47, vcc, 0, v121, vcc
	global_store_dwordx4 v[46:47], v[40:43], off
	v_pk_mul_f32 v[36:37], v[36:37], v[48:49] op_sel_hi:[1,0]
	s_mov_b64 s[0:1], 0x50000
	v_pk_mul_f32 v[40:41], v[34:35], v[48:49] op_sel_hi:[1,0]
	v_pk_mul_f32 v[34:35], v[32:33], v[48:49] op_sel_hi:[1,0]
	v_cvt_pk_bf16_f32 v32, v36, v37
	v_cvt_pk_bf16_f32 v33, v38, v39
	s_nop 0
	v_cvt_pk_bf16_f32 v34, v34, v35
	v_cvt_pk_bf16_f32 v35, v40, v41
	global_store_dwordx4 v[44:45], v[32:35], off offset:256
	s_nop 1
	v_mov_b32_e32 v32, v156
	v_pk_mul_f32 v[28:29], v[28:29], v[32:33] op_sel_hi:[1,0]
	v_pk_mul_f32 v[30:31], v[30:31], v[32:33] op_sel_hi:[1,0]
	v_pk_mul_f32 v[34:35], v[26:27], v[32:33] op_sel_hi:[1,0]
	v_pk_mul_f32 v[26:27], v[24:25], v[32:33] op_sel_hi:[1,0]
	v_cvt_pk_bf16_f32 v24, v28, v29
	v_lshl_add_u64 v[28:29], v[120:121], 0, s[0:1]
	s_mov_b32 s0, 0x50000
	v_cvt_pk_bf16_f32 v25, v30, v31
	v_add_co_u32_e32 v30, vcc, s0, v120
	v_cvt_pk_bf16_f32 v26, v26, v27
	v_cvt_pk_bf16_f32 v27, v34, v35
	v_pk_mul_f32 v[22:23], v[22:23], v[32:33] op_sel_hi:[1,0]
	s_nop 0
	v_addc_co_u32_e32 v31, vcc, 0, v121, vcc
	global_store_dwordx4 v[30:31], v[24:27], off
	v_pk_mul_f32 v[20:21], v[20:21], v[32:33] op_sel_hi:[1,0]
	s_mov_b64 s[0:1], 0x58000
	v_pk_mul_f32 v[24:25], v[18:19], v[32:33] op_sel_hi:[1,0]
	v_pk_mul_f32 v[18:19], v[16:17], v[32:33] op_sel_hi:[1,0]
	v_cvt_pk_bf16_f32 v16, v20, v21
	v_cvt_pk_bf16_f32 v17, v22, v23
	s_nop 0
	v_cvt_pk_bf16_f32 v18, v18, v19
	v_cvt_pk_bf16_f32 v19, v24, v25
	global_store_dwordx4 v[28:29], v[16:19], off offset:256
	s_nop 1
	v_mov_b32_e32 v16, v157
	v_pk_mul_f32 v[12:13], v[12:13], v[16:17] op_sel_hi:[1,0]
	v_pk_mul_f32 v[14:15], v[14:15], v[16:17] op_sel_hi:[1,0]
	v_pk_mul_f32 v[18:19], v[10:11], v[16:17] op_sel_hi:[1,0]
	v_pk_mul_f32 v[10:11], v[8:9], v[16:17] op_sel_hi:[1,0]
	v_cvt_pk_bf16_f32 v8, v12, v13
	v_lshl_add_u64 v[12:13], v[120:121], 0, s[0:1]
	s_mov_b32 s0, 0x58000
	v_cvt_pk_bf16_f32 v9, v14, v15
	v_add_co_u32_e32 v14, vcc, s0, v120
	v_cvt_pk_bf16_f32 v10, v10, v11
	v_cvt_pk_bf16_f32 v11, v18, v19
	s_mov_b64 s[0:1], -1
	s_nop 0
	v_addc_co_u32_e32 v15, vcc, 0, v121, vcc
	global_store_dwordx4 v[14:15], v[8:11], off
	s_andn2_b64 vcc, exec, s[6:7]
	v_pk_mul_f32 v[6:7], v[6:7], v[16:17] op_sel_hi:[1,0]
	v_pk_mul_f32 v[8:9], v[2:3], v[16:17] op_sel_hi:[1,0]
	v_pk_mul_f32 v[2:3], v[0:1], v[16:17] op_sel_hi:[1,0]
	v_pk_mul_f32 v[4:5], v[4:5], v[16:17] op_sel_hi:[1,0]
	s_nop 0
	v_cvt_pk_bf16_f32 v0, v4, v5
	v_cvt_pk_bf16_f32 v1, v6, v7
	v_cvt_pk_bf16_f32 v2, v2, v3
	v_cvt_pk_bf16_f32 v3, v8, v9
	global_store_dwordx4 v[12:13], v[0:3], off offset:256
	s_cbranch_vccnz .LBB0_844
	s_andn2_b64 vcc, exec, s[8:9]
	s_cbranch_vccnz .LBB0_843
	s_barrier
	s_branch .LBB0_843
